# v32 + w_out K-loop: compiler's loop-preheader vmcnt(0) (waited for the epilogue store acks every tile) dropped, matching the ff2 instance
# speedup vs baseline: 1.0020x; 1.0020x over previous
; template <class Epi>
; __device__ __forceinline__ void gemm_phase(LAS unsigned char* lds, const Gemm g, const StaticOrder& S, const Epi& E) {
;     ...
;         const bool has_next = S.next(ui + 1, nxt);
;         const char* nA = has_next ? (const char*)(nxt.alt ? g.A2 : g.A) + (size_t)nxt.pm * tA + (size_t)nxt.k0 * 2 : cA; const char* nB = has_next ? (const char*)(nxt.alt ? g.Bt2 : g.Bt) + (size_t)nxt.pn * tB + (size_t)nxt.k0 * 2 : cB;
;         const int nt = cur.nt;
;         for (int t = 0; t < nt; t += 2) {
;             const bool last = (t == nt - 2);
;             const char* a1 = cA + (size_t)(t + 1) * kstep;
;             const char* a2 = last ? nA : cA + (size_t)(t + 2) * kstep; const char* b2 = last ? nB : cB + (size_t)(t + 2) * kstep;
;             const char* a3 = a2 + kstep; const char* b3 = b2 + kstep;
;             PG8_LDB(B0, 0, 0); PG8_SCHED; PG8_LDA(At, 0, 0); PG8_STAGE(PG8_SA(1, 1), a1 + hA, voffA);
;             PG8_WAIT_L(8); PG8_BAR; PG8_WAIT_L(0); PG8_MMA(0, 0, At, B0); PG8_BAR; PG8_SCHED;
;             PG8_LDB(B1, 0, 1); PG8_STAGE(PG8_SB(0, 0), b2, voffB);
;             PG8_BAR; PG8_WAIT_L(0); PG8_MMA(0, 1, At, B1); PG8_BAR;
;             PG8_LDA(At, 0, 1); PG8_STAGE(PG8_SA(0, 0), a2, voffA);
;             PG8_BAR; PG8_WAIT_L(0); PG8_MMA(1, 0, At, B0); PG8_BAR; PG8_SCHED;
;             PG8_STAGE(PG8_SB(0, 1), b2 + hB, voffB);
;             PG8_WAIT_V(6); PG8_BAR; PG8_MMA(1, 1, At, B1); PG8_BAR;
;             PG8_LDB(B0, 1, 0); PG8_SCHED; PG8_LDA(At, 1, 0); PG8_STAGE(PG8_SA(0, 1), a2 + hA, voffA);
;             PG8_WAIT_L(8); PG8_BAR; PG8_WAIT_L(0); PG8_MMA(0, 0, At, B0); PG8_BAR; PG8_SCHED;
;             PG8_LDB(B1, 1, 1); PG8_STAGE(PG8_SB(1, 0), b3, voffB);
;             PG8_BAR; PG8_WAIT_L(0); PG8_MMA(0, 1, At, B1); PG8_BAR;
;             PG8_LDA(At, 1, 1); PG8_STAGE(PG8_SA(1, 0), a3, voffA);
;             PG8_BAR; PG8_WAIT_L(0); PG8_MMA(1, 0, At, B0); PG8_BAR; PG8_SCHED;
;             PG8_STAGE(PG8_SB(1, 1), b3 + hB, voffB);
;             PG8_WAIT_V(6); PG8_BAR; PG8_MMA(1, 1, At, B1); PG8_BAR;
;         }
;         if constexpr (Epi::HAS_PRE) { E(acc, cur, wr, wc, fr, fq, pre); if (has_next) E.pre(pre, nxt, wr, fr); } else E(acc, cur, wr, wc, fr, fq);
;         if (!has_next) break;
;         if (!(Epi::PAIRS && cur.alt == 0)) {
; #pragma unroll
;         for (int a = 0; a < 2; ++a)
; #pragma unroll
.LBB0_208:
	v_mov_b64_e32 v[2:3], 0x210
	s_ashr_i32 s59, s58, 31
	v_cmp_lt_i64_e32 vcc, s[60:61], v[2:3]
	s_lshl_b64 s[60:61], s[58:59], 19
	s_add_u32 s22, s6, s60
	s_addc_u32 s23, s7, s61
	s_ashr_i32 s45, s44, 31
	s_lshl_b64 s[62:63], s[44:45], 1
	s_add_u32 s60, s22, s62
	s_addc_u32 s61, s23, s63
	s_and_b64 s[74:75], vcc, exec
	s_cselect_b32 s33, s61, s69
	s_cselect_b32 s45, s60, s68
	s_ashr_i32 s57, s56, 31
	s_lshl_b64 s[74:75], s[56:57], 19
	s_add_u32 s22, s15, s74
	s_addc_u32 s23, s18, s75
	s_add_u32 s62, s22, s62
	s_addc_u32 s63, s23, s63
	s_and_b64 s[74:75], vcc, exec
	s_cselect_b32 s57, s63, s71
	s_cselect_b32 s59, s62, s70
	s_add_i32 s65, s30, -2
	s_add_u32 s68, s68, 0x40080
	s_addc_u32 s69, s69, 0
	s_add_u32 s67, s70, 0x100
	v_mov_b32_e32 v2, 0
	s_addc_u32 s97, s71, 0
	s_mov_b32 s70, 0
	v_mov_b32_e32 v3, v2
	v_mov_b32_e32 v4, v2
	v_mov_b32_e32 v5, v2
	v_mov_b32_e32 v6, v2
	v_mov_b32_e32 v7, v2
	v_mov_b32_e32 v8, v2
	v_mov_b32_e32 v9, v2
	v_mov_b32_e32 v18, v2
	v_mov_b32_e32 v19, v2
	v_mov_b32_e32 v20, v2
	v_mov_b32_e32 v21, v2
	v_mov_b32_e32 v22, v2
	v_mov_b32_e32 v23, v2
	v_mov_b32_e32 v24, v2
	v_mov_b32_e32 v25, v2
	v_mov_b32_e32 v34, v2
	v_mov_b32_e32 v35, v2
	v_mov_b32_e32 v36, v2
	v_mov_b32_e32 v37, v2
	v_mov_b32_e32 v38, v2
	v_mov_b32_e32 v39, v2
	v_mov_b32_e32 v40, v2
	v_mov_b32_e32 v41, v2
	v_mov_b32_e32 v50, v2
	v_mov_b32_e32 v51, v2
	v_mov_b32_e32 v52, v2
	v_mov_b32_e32 v53, v2
	v_mov_b32_e32 v54, v2
	v_mov_b32_e32 v55, v2
	v_mov_b32_e32 v56, v2
	v_mov_b32_e32 v57, v2
	v_mov_b32_e32 v10, v2
	v_mov_b32_e32 v11, v2
	v_mov_b32_e32 v12, v2
	v_mov_b32_e32 v13, v2
	v_mov_b32_e32 v14, v2
	v_mov_b32_e32 v15, v2
	v_mov_b32_e32 v16, v2
	v_mov_b32_e32 v17, v2
	v_mov_b32_e32 v26, v2
	v_mov_b32_e32 v27, v2
	v_mov_b32_e32 v28, v2
	v_mov_b32_e32 v29, v2
	v_mov_b32_e32 v30, v2
	v_mov_b32_e32 v31, v2
	v_mov_b32_e32 v32, v2
	v_mov_b32_e32 v33, v2
	v_mov_b32_e32 v42, v2
	v_mov_b32_e32 v43, v2
	v_mov_b32_e32 v44, v2
	v_mov_b32_e32 v45, v2
	v_mov_b32_e32 v46, v2
	v_mov_b32_e32 v47, v2
	v_mov_b32_e32 v48, v2
	v_mov_b32_e32 v49, v2
	v_mov_b32_e32 v58, v2
	v_mov_b32_e32 v59, v2
	v_mov_b32_e32 v60, v2
	v_mov_b32_e32 v61, v2
	v_mov_b32_e32 v62, v2
	v_mov_b32_e32 v63, v2
	v_mov_b32_e32 v64, v2
	v_mov_b32_e32 v65, v2
	v_mov_b32_e32 v66, v2
	v_mov_b32_e32 v67, v2
	v_mov_b32_e32 v68, v2
	v_mov_b32_e32 v69, v2
	v_mov_b32_e32 v70, v2
	v_mov_b32_e32 v71, v2
	v_mov_b32_e32 v72, v2
	v_mov_b32_e32 v73, v2
	v_mov_b32_e32 v82, v2
	v_mov_b32_e32 v83, v2
	v_mov_b32_e32 v84, v2
	v_mov_b32_e32 v85, v2
	v_mov_b32_e32 v86, v2
	v_mov_b32_e32 v87, v2
	v_mov_b32_e32 v88, v2
	v_mov_b32_e32 v89, v2
	v_mov_b32_e32 v98, v2
	v_mov_b32_e32 v99, v2
	v_mov_b32_e32 v100, v2
	v_mov_b32_e32 v101, v2
	v_mov_b32_e32 v102, v2
	v_mov_b32_e32 v103, v2
	v_mov_b32_e32 v104, v2
	v_mov_b32_e32 v105, v2
	v_mov_b32_e32 v114, v2
	v_mov_b32_e32 v115, v2
	v_mov_b32_e32 v116, v2
	v_mov_b32_e32 v117, v2
	v_mov_b32_e32 v118, v2
	v_mov_b32_e32 v119, v2
	v_mov_b32_e32 v120, v2
	v_mov_b32_e32 v121, v2
	v_mov_b32_e32 v74, v2
	v_mov_b32_e32 v75, v2
	v_mov_b32_e32 v76, v2
	v_mov_b32_e32 v77, v2
	v_mov_b32_e32 v78, v2
	v_mov_b32_e32 v79, v2
	v_mov_b32_e32 v80, v2
	v_mov_b32_e32 v81, v2
	v_mov_b32_e32 v90, v2
	v_mov_b32_e32 v91, v2
	v_mov_b32_e32 v92, v2
	v_mov_b32_e32 v93, v2
	v_mov_b32_e32 v94, v2
	v_mov_b32_e32 v95, v2
	v_mov_b32_e32 v96, v2
	v_mov_b32_e32 v97, v2
	v_mov_b32_e32 v106, v2
	v_mov_b32_e32 v107, v2
	v_mov_b32_e32 v108, v2
	v_mov_b32_e32 v109, v2
	v_mov_b32_e32 v110, v2
	v_mov_b32_e32 v111, v2
	v_mov_b32_e32 v112, v2
	v_mov_b32_e32 v113, v2
	v_mov_b32_e32 v122, v2
	v_mov_b32_e32 v123, v2
	v_mov_b32_e32 v124, v2
	v_mov_b32_e32 v125, v2
	v_mov_b32_e32 v126, v2
	v_mov_b32_e32 v127, v2
	v_mov_b32_e32 v128, v2
	v_mov_b32_e32 v129, v2
	v_add_u32_e32 v218, 0x10000, v188
	ds_read_b128 v[130:133], v218
	ds_read_b128 v[134:137], v218 offset:1024
	ds_read_b128 v[138:141], v218 offset:2048
	ds_read_b128 v[142:145], v218 offset:3072
